# out-proj epilogue rewritten by hand: 32 serialised x-residual load-wait-use round trips become two batches of 16 loads with counted vmcnt waits, scalar-base addressing, row sums by permlane swaps
# speedup vs baseline: 1.0190x; 1.0018x over previous
; #define LAS __attribute__((address_space(3)))
; DI u32x2 pk4(f32x4 v) { u32x2 r; r.x = pk2(v[0], v[1]); r.y = pk2(v[2], v[3]); return r; }
;     DI void operator()(const AccT& acc, const Unit& u, int wr, int wc, int fr, int fq, LAS unsigned char*) const {
;         const int col0 = u.pn * 256 + wc * 32 + 4 * fq;
; #pragma unroll
;         for (int ai = 0; ai < 2; ++ai)
; #pragma unroll
;             for (int m = 0; m < 4; ++m) {
;                 const int row = u.pm * 256 + ai * 128 + wr * 64 + m * 16 + fr;
;                 const float* xr = (row < SEQ ? xp + (size_t)row * DM : xs + (size_t)(row - SEQ) * DM) + col0;
;                 bf16_t* brow = X1B + (size_t)(row < SEQ ? row + 2 : row + (X1B_PROMPT_ROWS - SEQ)) * DM + col0;
;                 float ss = 0.f;
; #pragma unroll
;                 for (int bj = 0; bj < 2; ++bj)
; #pragma unroll
;                     for (int n = 0; n < 2; ++n) {
;                         const int c = bj * 128 + n * 16;
;                         const f32x4 o = *(const f32x4*)(xr + c) + acc[ai][bj][m][n];
;                         *(u32x2*)(brow + c) = pk4(o);
;                         ss += (o[0] * o[0] + o[1] * o[1]) + (o[2] * o[2] + o[3] * o[3]);
;                     }
;                 ss += __shfl_xor(ss, 16); ss += __shfl_xor(ss, 32);
;                 if (fq == 0) unsafeAtomicAdd(sumsq + row, ss);
;             }
;     }
.LBB0_960:
	v_lshl_add_u32 v130, s31, 8, v132
	v_lshl_or_b32 v128, s33, 8, v134
	s_cmp_lt_i32 s31, 64
	s_cselect_b32 s16, s44, s46
	s_cselect_b32 s17, s45, s47
	s_cselect_b32 s42, 0, 0x4000000
	s_cselect_b32 s43, 1, 64
	s_lshl_b32 s43, s43, 12
	s_sub_u32 s16, s16, s42
	s_subb_u32 s17, s17, 0
	s_add_u32 s18, s56, s43
	s_addc_u32 s19, s57, 0
	v_lshlrev_b32_e32 v129, 12, v130
	v_lshlrev_b32_e32 v131, 11, v130
	v_lshl_add_u32 v129, v128, 2, v129
	v_lshl_add_u32 v131, v128, 1, v131
	v_lshlrev_b32_e32 v130, 2, v130
	global_load_dwordx4 v[146:149], v129, s[16:17]
	global_load_dwordx4 v[150:153], v129, s[16:17] offset:64
	global_load_dwordx4 v[154:157], v129, s[16:17] offset:512
	global_load_dwordx4 v[158:161], v129, s[16:17] offset:576
	s_add_u32 s36, s16, 0x10000
	s_addc_u32 s37, s17, 0
	global_load_dwordx4 v[182:185], v129, s[36:37]
	global_load_dwordx4 v[186:189], v129, s[36:37] offset:64
	global_load_dwordx4 v[190:193], v129, s[36:37] offset:512
	global_load_dwordx4 v[194:197], v129, s[36:37] offset:576
	s_add_u32 s36, s16, 0x20000
	s_addc_u32 s37, s17, 0
	global_load_dwordx4 v[198:201], v129, s[36:37]
	global_load_dwordx4 v[202:205], v129, s[36:37] offset:64
	global_load_dwordx4 v[206:209], v129, s[36:37] offset:512
	global_load_dwordx4 v[210:213], v129, s[36:37] offset:576
	s_add_u32 s36, s16, 0x30000
	s_addc_u32 s37, s17, 0
	global_load_dwordx4 v[162:165], v129, s[36:37]
	global_load_dwordx4 v[214:217], v129, s[36:37] offset:64
	global_load_dwordx4 v[136:139], v129, s[36:37] offset:512
	global_load_dwordx4 v[140:143], v129, s[36:37] offset:576
	s_waitcnt vmcnt(12)
	v_pk_add_f32 v[146:147], v[124:125], v[146:147]
	v_pk_add_f32 v[148:149], v[126:127], v[148:149]
	v_pk_add_f32 v[150:151], v[120:121], v[150:151]
	v_pk_add_f32 v[152:153], v[122:123], v[152:153]
	v_pk_add_f32 v[154:155], v[116:117], v[154:155]
	v_pk_add_f32 v[156:157], v[118:119], v[156:157]
	v_pk_add_f32 v[158:159], v[112:113], v[158:159]
	v_pk_add_f32 v[160:161], v[114:115], v[160:161]
	s_add_u32 s36, s16, 0x80000
	s_addc_u32 s37, s17, 0
	global_load_dwordx4 v[124:127], v129, s[36:37]
	global_load_dwordx4 v[120:123], v129, s[36:37] offset:64
	global_load_dwordx4 v[116:119], v129, s[36:37] offset:512
	global_load_dwordx4 v[112:115], v129, s[36:37] offset:576
	s_waitcnt vmcnt(12)
	v_pk_add_f32 v[182:183], v[108:109], v[182:183]
	v_pk_add_f32 v[184:185], v[110:111], v[184:185]
	v_pk_add_f32 v[186:187], v[104:105], v[186:187]
	v_pk_add_f32 v[188:189], v[106:107], v[188:189]
	v_pk_add_f32 v[190:191], v[100:101], v[190:191]
	v_pk_add_f32 v[192:193], v[102:103], v[192:193]
	v_pk_add_f32 v[194:195], v[96:97], v[194:195]
	v_pk_add_f32 v[196:197], v[98:99], v[196:197]
	s_add_u32 s36, s16, 0x90000
	s_addc_u32 s37, s17, 0
	global_load_dwordx4 v[108:111], v129, s[36:37]
	global_load_dwordx4 v[104:107], v129, s[36:37] offset:64
	global_load_dwordx4 v[100:103], v129, s[36:37] offset:512
	global_load_dwordx4 v[96:99], v129, s[36:37] offset:576
	s_waitcnt vmcnt(12)
	v_pk_add_f32 v[198:199], v[92:93], v[198:199]
	v_pk_add_f32 v[200:201], v[94:95], v[200:201]
	v_pk_add_f32 v[202:203], v[88:89], v[202:203]
	v_pk_add_f32 v[204:205], v[90:91], v[204:205]
	v_pk_add_f32 v[206:207], v[84:85], v[206:207]
	v_pk_add_f32 v[208:209], v[86:87], v[208:209]
	v_pk_add_f32 v[210:211], v[80:81], v[210:211]
	v_pk_add_f32 v[212:213], v[82:83], v[212:213]
	s_add_u32 s36, s16, 0xa0000
	s_addc_u32 s37, s17, 0
	global_load_dwordx4 v[92:95], v129, s[36:37]
	global_load_dwordx4 v[88:91], v129, s[36:37] offset:64
	global_load_dwordx4 v[84:87], v129, s[36:37] offset:512
	global_load_dwordx4 v[80:83], v129, s[36:37] offset:576
	s_waitcnt vmcnt(12)
	v_pk_add_f32 v[162:163], v[76:77], v[162:163]
	v_pk_add_f32 v[164:165], v[78:79], v[164:165]
	v_pk_add_f32 v[214:215], v[72:73], v[214:215]
	v_pk_add_f32 v[216:217], v[74:75], v[216:217]
	v_pk_add_f32 v[136:137], v[68:69], v[136:137]
	v_pk_add_f32 v[138:139], v[70:71], v[138:139]
	v_pk_add_f32 v[140:141], v[64:65], v[140:141]
	v_pk_add_f32 v[142:143], v[66:67], v[142:143]
	s_add_u32 s36, s16, 0xb0000
	s_addc_u32 s37, s17, 0
	global_load_dwordx4 v[76:79], v129, s[36:37]
	global_load_dwordx4 v[72:75], v129, s[36:37] offset:64
	global_load_dwordx4 v[68:71], v129, s[36:37] offset:512
	global_load_dwordx4 v[64:67], v129, s[36:37] offset:576
	v_pk_mul_f32 v[166:167], v[146:147], v[146:147]
	v_pk_mul_f32 v[144:145], v[148:149], v[148:149]
	v_pk_fma_f32 v[166:167], v[150:151], v[150:151], v[166:167]
	v_pk_fma_f32 v[144:145], v[152:153], v[152:153], v[144:145]
	v_pk_fma_f32 v[166:167], v[154:155], v[154:155], v[166:167]
	v_pk_fma_f32 v[144:145], v[156:157], v[156:157], v[144:145]
	v_pk_fma_f32 v[166:167], v[158:159], v[158:159], v[166:167]
	v_pk_fma_f32 v[144:145], v[160:161], v[160:161], v[144:145]
	s_nop 0
	v_pk_add_f32 v[166:167], v[166:167], v[144:145]
	v_cvt_pk_bf16_f32 v146, v146, v147
	v_cvt_pk_bf16_f32 v147, v148, v149
	v_cvt_pk_bf16_f32 v150, v150, v151
	v_cvt_pk_bf16_f32 v151, v152, v153
	v_cvt_pk_bf16_f32 v154, v154, v155
	v_cvt_pk_bf16_f32 v155, v156, v157
	v_cvt_pk_bf16_f32 v158, v158, v159
	v_cvt_pk_bf16_f32 v159, v160, v161
	v_add_f32_e32 v218, v166, v167
	global_store_dwordx2 v131, v[146:147], s[18:19]
	global_store_dwordx2 v131, v[150:151], s[18:19] offset:32
	global_store_dwordx2 v131, v[154:155], s[18:19] offset:256
	global_store_dwordx2 v131, v[158:159], s[18:19] offset:288
	v_mov_b32_e32 v219, v218
	s_nop 1
	v_permlane16_swap_b32_e32 v219, v218
	v_add_f32_e32 v218, v218, v219
	v_mov_b32_e32 v219, v218
	s_nop 1
	v_permlane32_swap_b32_e32 v219, v218
	v_add_f32_e32 v218, v218, v219
	s_and_saveexec_b64 s[0:1], s[40:41]
	global_atomic_add_f32 v130, v218, s[58:59]
; #define LAS __attribute__((address_space(3)))
; DI u32x2 pk4(f32x4 v) { u32x2 r; r.x = pk2(v[0], v[1]); r.y = pk2(v[2], v[3]); return r; }
;     DI void operator()(const AccT& acc, const Unit& u, int wr, int wc, int fr, int fq, LAS unsigned char*) const {
;         const int col0 = u.pn * 256 + wc * 32 + 4 * fq;
; #pragma unroll
;         for (int ai = 0; ai < 2; ++ai)
; #pragma unroll
;             for (int m = 0; m < 4; ++m) {
;                 const int row = u.pm * 256 + ai * 128 + wr * 64 + m * 16 + fr;
;                 const float* xr = (row < SEQ ? xp + (size_t)row * DM : xs + (size_t)(row - SEQ) * DM) + col0;
;                 bf16_t* brow = X1B + (size_t)(row < SEQ ? row + 2 : row + (X1B_PROMPT_ROWS - SEQ)) * DM + col0;
;                 float ss = 0.f;
; #pragma unroll
;                 for (int bj = 0; bj < 2; ++bj)
; #pragma unroll
;                     for (int n = 0; n < 2; ++n) {
;                         const int c = bj * 128 + n * 16;
;                         const f32x4 o = *(const f32x4*)(xr + c) + acc[ai][bj][m][n];
;                         *(u32x2*)(brow + c) = pk4(o);
;                         ss += (o[0] * o[0] + o[1] * o[1]) + (o[2] * o[2] + o[3] * o[3]);
;                     }
;                 ss += __shfl_xor(ss, 16); ss += __shfl_xor(ss, 32);
;                 if (fq == 0) unsafeAtomicAdd(sumsq + row, ss);
;             }
;     }
	s_mov_b64 exec, s[0:1]
	v_pk_mul_f32 v[166:167], v[182:183], v[182:183]
	v_pk_mul_f32 v[144:145], v[184:185], v[184:185]
	v_pk_fma_f32 v[166:167], v[186:187], v[186:187], v[166:167]
	v_pk_fma_f32 v[144:145], v[188:189], v[188:189], v[144:145]
	v_pk_fma_f32 v[166:167], v[190:191], v[190:191], v[166:167]
	v_pk_fma_f32 v[144:145], v[192:193], v[192:193], v[144:145]
	v_pk_fma_f32 v[166:167], v[194:195], v[194:195], v[166:167]
	v_pk_fma_f32 v[144:145], v[196:197], v[196:197], v[144:145]
	s_nop 0
	v_pk_add_f32 v[166:167], v[166:167], v[144:145]
	s_add_u32 s48, s18, 0x8000
	s_addc_u32 s49, s19, 0
	v_cvt_pk_bf16_f32 v182, v182, v183
	v_cvt_pk_bf16_f32 v183, v184, v185
	v_cvt_pk_bf16_f32 v186, v186, v187
	v_cvt_pk_bf16_f32 v187, v188, v189
	v_cvt_pk_bf16_f32 v190, v190, v191
	v_cvt_pk_bf16_f32 v191, v192, v193
	v_cvt_pk_bf16_f32 v194, v194, v195
	v_cvt_pk_bf16_f32 v195, v196, v197
	v_add_f32_e32 v218, v166, v167
	global_store_dwordx2 v131, v[182:183], s[48:49]
	global_store_dwordx2 v131, v[186:187], s[48:49] offset:32
	global_store_dwordx2 v131, v[190:191], s[48:49] offset:256
	global_store_dwordx2 v131, v[194:195], s[48:49] offset:288
	v_mov_b32_e32 v219, v218
	s_nop 1
	v_permlane16_swap_b32_e32 v219, v218
	v_add_f32_e32 v218, v218, v219
	v_mov_b32_e32 v219, v218
	s_nop 1
	v_permlane32_swap_b32_e32 v219, v218
	v_add_f32_e32 v218, v218, v219
	s_and_saveexec_b64 s[0:1], s[40:41]
	global_atomic_add_f32 v130, v218, s[58:59] offset:64
	s_mov_b64 exec, s[0:1]
	v_pk_mul_f32 v[166:167], v[198:199], v[198:199]
	v_pk_mul_f32 v[144:145], v[200:201], v[200:201]
	v_pk_fma_f32 v[166:167], v[202:203], v[202:203], v[166:167]
	v_pk_fma_f32 v[144:145], v[204:205], v[204:205], v[144:145]
	v_pk_fma_f32 v[166:167], v[206:207], v[206:207], v[166:167]
	v_pk_fma_f32 v[144:145], v[208:209], v[208:209], v[144:145]
	v_pk_fma_f32 v[166:167], v[210:211], v[210:211], v[166:167]
	v_pk_fma_f32 v[144:145], v[212:213], v[212:213], v[144:145]
	s_nop 0
	v_pk_add_f32 v[166:167], v[166:167], v[144:145]
	s_add_u32 s48, s18, 0x10000
	s_addc_u32 s49, s19, 0
	v_cvt_pk_bf16_f32 v198, v198, v199
	v_cvt_pk_bf16_f32 v199, v200, v201
	v_cvt_pk_bf16_f32 v202, v202, v203
	v_cvt_pk_bf16_f32 v203, v204, v205
	v_cvt_pk_bf16_f32 v206, v206, v207
	v_cvt_pk_bf16_f32 v207, v208, v209
	v_cvt_pk_bf16_f32 v210, v210, v211
	v_cvt_pk_bf16_f32 v211, v212, v213
	v_add_f32_e32 v218, v166, v167
	global_store_dwordx2 v131, v[198:199], s[48:49]
	global_store_dwordx2 v131, v[202:203], s[48:49] offset:32
	global_store_dwordx2 v131, v[206:207], s[48:49] offset:256
	global_store_dwordx2 v131, v[210:211], s[48:49] offset:288
	v_mov_b32_e32 v219, v218
	s_nop 1
	v_permlane16_swap_b32_e32 v219, v218
	v_add_f32_e32 v218, v218, v219
	v_mov_b32_e32 v219, v218
	s_nop 1
	v_permlane32_swap_b32_e32 v219, v218
	v_add_f32_e32 v218, v218, v219
	s_and_saveexec_b64 s[0:1], s[40:41]
	global_atomic_add_f32 v130, v218, s[58:59] offset:128
	s_mov_b64 exec, s[0:1]
	v_pk_mul_f32 v[166:167], v[162:163], v[162:163]
	v_pk_mul_f32 v[144:145], v[164:165], v[164:165]
	v_pk_fma_f32 v[166:167], v[214:215], v[214:215], v[166:167]
	v_pk_fma_f32 v[144:145], v[216:217], v[216:217], v[144:145]
	v_pk_fma_f32 v[166:167], v[136:137], v[136:137], v[166:167]
	v_pk_fma_f32 v[144:145], v[138:139], v[138:139], v[144:145]
	v_pk_fma_f32 v[166:167], v[140:141], v[140:141], v[166:167]
	v_pk_fma_f32 v[144:145], v[142:143], v[142:143], v[144:145]
	s_nop 0
	v_pk_add_f32 v[166:167], v[166:167], v[144:145]
	s_add_u32 s48, s18, 0x18000
	s_addc_u32 s49, s19, 0
	v_cvt_pk_bf16_f32 v162, v162, v163
	v_cvt_pk_bf16_f32 v163, v164, v165
	v_cvt_pk_bf16_f32 v214, v214, v215
	v_cvt_pk_bf16_f32 v215, v216, v217
	v_cvt_pk_bf16_f32 v136, v136, v137
	v_cvt_pk_bf16_f32 v137, v138, v139
	v_cvt_pk_bf16_f32 v140, v140, v141
	v_cvt_pk_bf16_f32 v141, v142, v143
	v_add_f32_e32 v218, v166, v167
	global_store_dwordx2 v131, v[162:163], s[48:49]
	global_store_dwordx2 v131, v[214:215], s[48:49] offset:32
	global_store_dwordx2 v131, v[136:137], s[48:49] offset:256
	global_store_dwordx2 v131, v[140:141], s[48:49] offset:288
	v_mov_b32_e32 v219, v218
	s_nop 1
	v_permlane16_swap_b32_e32 v219, v218
	v_add_f32_e32 v218, v218, v219
	v_mov_b32_e32 v219, v218
	s_nop 1
	v_permlane32_swap_b32_e32 v219, v218
	v_add_f32_e32 v218, v218, v219
	s_and_saveexec_b64 s[0:1], s[40:41]
	global_atomic_add_f32 v130, v218, s[58:59] offset:192
	s_mov_b64 exec, s[0:1]
	s_waitcnt vmcnt(32)
	v_pk_add_f32 v[124:125], v[60:61], v[124:125]
	v_pk_add_f32 v[126:127], v[62:63], v[126:127]
	v_pk_add_f32 v[120:121], v[56:57], v[120:121]
	v_pk_add_f32 v[122:123], v[58:59], v[122:123]
	v_pk_add_f32 v[116:117], v[52:53], v[116:117]
	v_pk_add_f32 v[118:119], v[54:55], v[118:119]
	v_pk_add_f32 v[112:113], v[48:49], v[112:113]
	v_pk_add_f32 v[114:115], v[50:51], v[114:115]
	v_pk_mul_f32 v[166:167], v[124:125], v[124:125]
	v_pk_mul_f32 v[144:145], v[126:127], v[126:127]
	v_pk_fma_f32 v[166:167], v[120:121], v[120:121], v[166:167]
	v_pk_fma_f32 v[144:145], v[122:123], v[122:123], v[144:145]
	v_pk_fma_f32 v[166:167], v[116:117], v[116:117], v[166:167]
	v_pk_fma_f32 v[144:145], v[118:119], v[118:119], v[144:145]
	v_pk_fma_f32 v[166:167], v[112:113], v[112:113], v[166:167]
	v_pk_fma_f32 v[144:145], v[114:115], v[114:115], v[144:145]
	s_nop 0
	v_pk_add_f32 v[166:167], v[166:167], v[144:145]
	s_add_u32 s48, s18, 0x40000
	s_addc_u32 s49, s19, 0
	v_cvt_pk_bf16_f32 v124, v124, v125
	v_cvt_pk_bf16_f32 v125, v126, v127
	v_cvt_pk_bf16_f32 v120, v120, v121
	v_cvt_pk_bf16_f32 v121, v122, v123
	v_cvt_pk_bf16_f32 v116, v116, v117
	v_cvt_pk_bf16_f32 v117, v118, v119
	v_cvt_pk_bf16_f32 v112, v112, v113
	v_cvt_pk_bf16_f32 v113, v114, v115
	v_add_f32_e32 v218, v166, v167
	global_store_dwordx2 v131, v[124:125], s[48:49]
	global_store_dwordx2 v131, v[120:121], s[48:49] offset:32
	global_store_dwordx2 v131, v[116:117], s[48:49] offset:256
	global_store_dwordx2 v131, v[112:113], s[48:49] offset:288
	v_mov_b32_e32 v219, v218
	s_nop 1
	v_permlane16_swap_b32_e32 v219, v218
	v_add_f32_e32 v218, v218, v219
	v_mov_b32_e32 v219, v218
	s_nop 1
	v_permlane32_swap_b32_e32 v219, v218
	v_add_f32_e32 v218, v218, v219
	s_and_saveexec_b64 s[0:1], s[40:41]
	global_atomic_add_f32 v130, v218, s[58:59] offset:512
	s_mov_b64 exec, s[0:1]
	s_waitcnt vmcnt(33)
; #define LAS __attribute__((address_space(3)))
; DI u32x2 pk4(f32x4 v) { u32x2 r; r.x = pk2(v[0], v[1]); r.y = pk2(v[2], v[3]); return r; }
;     DI void operator()(const AccT& acc, const Unit& u, int wr, int wc, int fr, int fq, LAS unsigned char*) const {
;         const int col0 = u.pn * 256 + wc * 32 + 4 * fq;
; #pragma unroll
;         for (int ai = 0; ai < 2; ++ai)
; #pragma unroll
;             for (int m = 0; m < 4; ++m) {
;                 const int row = u.pm * 256 + ai * 128 + wr * 64 + m * 16 + fr;
;                 const float* xr = (row < SEQ ? xp + (size_t)row * DM : xs + (size_t)(row - SEQ) * DM) + col0;
;                 bf16_t* brow = X1B + (size_t)(row < SEQ ? row + 2 : row + (X1B_PROMPT_ROWS - SEQ)) * DM + col0;
;                 float ss = 0.f;
; #pragma unroll
;                 for (int bj = 0; bj < 2; ++bj)
; #pragma unroll
;                     for (int n = 0; n < 2; ++n) {
;                         const int c = bj * 128 + n * 16;
;                         const f32x4 o = *(const f32x4*)(xr + c) + acc[ai][bj][m][n];
;                         *(u32x2*)(brow + c) = pk4(o);
;                         ss += (o[0] * o[0] + o[1] * o[1]) + (o[2] * o[2] + o[3] * o[3]);
;                     }
;                 ss += __shfl_xor(ss, 16); ss += __shfl_xor(ss, 32);
;                 if (fq == 0) unsafeAtomicAdd(sumsq + row, ss);
;             }
;     }
	v_pk_add_f32 v[108:109], v[44:45], v[108:109]
	v_pk_add_f32 v[110:111], v[46:47], v[110:111]
	v_pk_add_f32 v[104:105], v[40:41], v[104:105]
	v_pk_add_f32 v[106:107], v[42:43], v[106:107]
	v_pk_add_f32 v[100:101], v[36:37], v[100:101]
	v_pk_add_f32 v[102:103], v[38:39], v[102:103]
	v_pk_add_f32 v[96:97], v[32:33], v[96:97]
	v_pk_add_f32 v[98:99], v[34:35], v[98:99]
	v_pk_mul_f32 v[166:167], v[108:109], v[108:109]
	v_pk_mul_f32 v[144:145], v[110:111], v[110:111]
	v_pk_fma_f32 v[166:167], v[104:105], v[104:105], v[166:167]
	v_pk_fma_f32 v[144:145], v[106:107], v[106:107], v[144:145]
	v_pk_fma_f32 v[166:167], v[100:101], v[100:101], v[166:167]
	v_pk_fma_f32 v[144:145], v[102:103], v[102:103], v[144:145]
	v_pk_fma_f32 v[166:167], v[96:97], v[96:97], v[166:167]
	v_pk_fma_f32 v[144:145], v[98:99], v[98:99], v[144:145]
	s_nop 0
	v_pk_add_f32 v[166:167], v[166:167], v[144:145]
	s_add_u32 s48, s18, 0x48000
	s_addc_u32 s49, s19, 0
	v_cvt_pk_bf16_f32 v108, v108, v109
	v_cvt_pk_bf16_f32 v109, v110, v111
	v_cvt_pk_bf16_f32 v104, v104, v105
	v_cvt_pk_bf16_f32 v105, v106, v107
	v_cvt_pk_bf16_f32 v100, v100, v101
	v_cvt_pk_bf16_f32 v101, v102, v103
	v_cvt_pk_bf16_f32 v96, v96, v97
	v_cvt_pk_bf16_f32 v97, v98, v99
	v_add_f32_e32 v218, v166, v167
	global_store_dwordx2 v131, v[108:109], s[48:49]
	global_store_dwordx2 v131, v[104:105], s[48:49] offset:32
	global_store_dwordx2 v131, v[100:101], s[48:49] offset:256
	global_store_dwordx2 v131, v[96:97], s[48:49] offset:288
	v_mov_b32_e32 v219, v218
	s_nop 1
	v_permlane16_swap_b32_e32 v219, v218
	v_add_f32_e32 v218, v218, v219
	v_mov_b32_e32 v219, v218
	s_nop 1
	v_permlane32_swap_b32_e32 v219, v218
	v_add_f32_e32 v218, v218, v219
	s_and_saveexec_b64 s[0:1], s[40:41]
	global_atomic_add_f32 v130, v218, s[58:59] offset:576
	s_mov_b64 exec, s[0:1]
	s_waitcnt vmcnt(34)
	v_pk_add_f32 v[92:93], v[28:29], v[92:93]
	v_pk_add_f32 v[94:95], v[30:31], v[94:95]
	v_pk_add_f32 v[88:89], v[24:25], v[88:89]
	v_pk_add_f32 v[90:91], v[26:27], v[90:91]
	v_pk_add_f32 v[84:85], v[20:21], v[84:85]
	v_pk_add_f32 v[86:87], v[22:23], v[86:87]
	v_pk_add_f32 v[80:81], v[16:17], v[80:81]
	v_pk_add_f32 v[82:83], v[18:19], v[82:83]
	v_pk_mul_f32 v[166:167], v[92:93], v[92:93]
	v_pk_mul_f32 v[144:145], v[94:95], v[94:95]
	v_pk_fma_f32 v[166:167], v[88:89], v[88:89], v[166:167]
	v_pk_fma_f32 v[144:145], v[90:91], v[90:91], v[144:145]
	v_pk_fma_f32 v[166:167], v[84:85], v[84:85], v[166:167]
	v_pk_fma_f32 v[144:145], v[86:87], v[86:87], v[144:145]
	v_pk_fma_f32 v[166:167], v[80:81], v[80:81], v[166:167]
	v_pk_fma_f32 v[144:145], v[82:83], v[82:83], v[144:145]
	s_nop 0
	v_pk_add_f32 v[166:167], v[166:167], v[144:145]
	s_add_u32 s48, s18, 0x50000
	s_addc_u32 s49, s19, 0
	v_cvt_pk_bf16_f32 v92, v92, v93
	v_cvt_pk_bf16_f32 v93, v94, v95
	v_cvt_pk_bf16_f32 v88, v88, v89
	v_cvt_pk_bf16_f32 v89, v90, v91
	v_cvt_pk_bf16_f32 v84, v84, v85
	v_cvt_pk_bf16_f32 v85, v86, v87
	v_cvt_pk_bf16_f32 v80, v80, v81
	v_cvt_pk_bf16_f32 v81, v82, v83
	v_add_f32_e32 v218, v166, v167
	global_store_dwordx2 v131, v[92:93], s[48:49]
	global_store_dwordx2 v131, v[88:89], s[48:49] offset:32
	global_store_dwordx2 v131, v[84:85], s[48:49] offset:256
	global_store_dwordx2 v131, v[80:81], s[48:49] offset:288
	v_mov_b32_e32 v219, v218
	s_nop 1
	v_permlane16_swap_b32_e32 v219, v218
	v_add_f32_e32 v218, v218, v219
	v_mov_b32_e32 v219, v218
	s_nop 1
	v_permlane32_swap_b32_e32 v219, v218
	v_add_f32_e32 v218, v218, v219
	s_and_saveexec_b64 s[0:1], s[40:41]
	global_atomic_add_f32 v130, v218, s[58:59] offset:640
	s_mov_b64 exec, s[0:1]
	s_waitcnt vmcnt(35)
	v_pk_add_f32 v[76:77], v[12:13], v[76:77]
	v_pk_add_f32 v[78:79], v[14:15], v[78:79]
	v_pk_add_f32 v[72:73], v[8:9], v[72:73]
	v_pk_add_f32 v[74:75], v[10:11], v[74:75]
	v_pk_add_f32 v[68:69], v[4:5], v[68:69]
	v_pk_add_f32 v[70:71], v[6:7], v[70:71]
	v_pk_add_f32 v[64:65], v[0:1], v[64:65]
	v_pk_add_f32 v[66:67], v[2:3], v[66:67]
	v_pk_mul_f32 v[166:167], v[76:77], v[76:77]
	v_pk_mul_f32 v[144:145], v[78:79], v[78:79]
	v_pk_fma_f32 v[166:167], v[72:73], v[72:73], v[166:167]
	v_pk_fma_f32 v[144:145], v[74:75], v[74:75], v[144:145]
	v_pk_fma_f32 v[166:167], v[68:69], v[68:69], v[166:167]
	v_pk_fma_f32 v[144:145], v[70:71], v[70:71], v[144:145]
	v_pk_fma_f32 v[166:167], v[64:65], v[64:65], v[166:167]
	v_pk_fma_f32 v[144:145], v[66:67], v[66:67], v[144:145]
	s_nop 0
	v_pk_add_f32 v[166:167], v[166:167], v[144:145]
	s_add_u32 s48, s18, 0x58000
	s_addc_u32 s49, s19, 0
	v_cvt_pk_bf16_f32 v76, v76, v77
	v_cvt_pk_bf16_f32 v77, v78, v79
	v_cvt_pk_bf16_f32 v72, v72, v73
	v_cvt_pk_bf16_f32 v73, v74, v75
	v_cvt_pk_bf16_f32 v68, v68, v69
	v_cvt_pk_bf16_f32 v69, v70, v71
	v_cvt_pk_bf16_f32 v64, v64, v65
	v_cvt_pk_bf16_f32 v65, v66, v67
	v_add_f32_e32 v218, v166, v167
	global_store_dwordx2 v131, v[76:77], s[48:49]
	global_store_dwordx2 v131, v[72:73], s[48:49] offset:32
	global_store_dwordx2 v131, v[68:69], s[48:49] offset:256
	global_store_dwordx2 v131, v[64:65], s[48:49] offset:288
	v_mov_b32_e32 v219, v218
	s_nop 1
	v_permlane16_swap_b32_e32 v219, v218
	v_add_f32_e32 v218, v218, v219
	v_mov_b32_e32 v219, v218
	s_nop 1
	v_permlane32_swap_b32_e32 v219, v218
	v_add_f32_e32 v218, v218, v219
	s_and_saveexec_b64 s[0:1], s[40:41]
	global_atomic_add_f32 v130, v218, s[58:59] offset:704
	s_mov_b64 exec, s[0:1]
	s_cmp_eq_u32 s30, s28
	s_mov_b64 s[0:1], -1
	s_cbranch_scc1 .LBB0_955
